# indexer score loop: K-tile prefetch waited at copy instead of before MFMAs
# speedup vs baseline: 1.0080x; 1.0017x over previous
; __device__ __forceinline__ void indexer_phase(const bf16_t* PJ, float* rk, unsigned short* SEL, LAS unsigned char* lds) {
;     ...
;             const int g = r32 >> 3, hp = (r32 >> 2) & 1, ii = r32 & 3, tq = 2 * hp + (g >> 1), head = 4 * (g & 1) + ii;
;             bf16x8 af[2][4]; float wq[2][2][8];
; #pragma unroll
;             for (int rt = 0; rt < 2; ++rt) {
;                 const bf16_t* qp = PJ + (rowbase + t0 + 4 * rt + tq) * PROJ_LD + PJ_QI + head * 64 + hi * 8;
; #pragma unroll
;                 for (int kk = 0; kk < 4; ++kk) af[rt][kk] = *(const bf16x8*)(qp + kk * 16);
; #pragma unroll
;                 for (int qq = 0; qq < 2; ++qq) { const u32x4 w = *(const u32x4*)(PJ + (rowbase + t0 + 4 * rt + 2 * hi + qq) * PROJ_LD + PJ_WI);
;                     const float sc = 0.35355339059327373f;
;                     wq[rt][qq][0] = bflo(w.x) * sc; wq[rt][qq][1] = bfhi(w.x) * sc; wq[rt][qq][2] = bflo(w.y) * sc; wq[rt][qq][3] = bfhi(w.y) * sc;
;                     wq[rt][qq][4] = bflo(w.z) * sc; wq[rt][qq][5] = bfhi(w.z) * sc; wq[rt][qq][6] = bflo(w.w) * sc; wq[rt][qq][7] = bfhi(w.w) * sc; }
;             }
;             float rmax[2][2], rmin[2][2];
; #pragma unroll
;             for (int rt = 0; rt < 2; ++rt)
; #pragma unroll
;                 for (int qq = 0; qq < 2; ++qq) { rmax[rt][qq] = -INFINITY; rmin[rt][qq] = INFINITY; }
;             const int nkt = (t0 + 8 + 31) >> 5;
;             const bf16_t* kbase = PJ + (rowbase + r32) * PROJ_LD + PJ_KI + hi * 8;
;             bf16x8 bcur[4], bnxt[4];
;             int kt = wid;
; #pragma unroll
;             for (int kk = 0; kk < 4; ++kk) bcur[kk] = *(const bf16x8*)(kbase + (size_t)(32 * kt) * PROJ_LD + kk * 16);
.LBB0_864:
	s_and_b32 s0, s2, 0x1ff
	s_ashr_i32 s24, s2, 9
	s_sub_i32 s1, 0x2ff, s0
	s_cmpk_lt_u32 s0, 0x100
	s_cselect_b32 s0, s0, s1
	s_lshl_b32 s1, s0, 3
	s_ashr_i32 s25, s24, 31
	s_add_i32 s77, s1, s33
	s_lshl_b64 s[26:27], s[24:25], 12
	s_ashr_i32 s3, s77, 31
	s_add_u32 s24, s26, s77
	s_addc_u32 s25, s27, s3
	s_lshl_b64 s[24:25], s[24:25], 9
	s_add_u32 s60, s4, s24
	s_addc_u32 s61, s5, s25
	s_cmp_gt_u32 s0, 31
	s_mov_b64 s[24:25], -1
	s_cbranch_scc0 .LBB0_1027
	s_add_i32 s0, s1, 39
	s_lshr_b32 s0, s0, 5
	s_cmp_ge_i32 s33, s0
	s_cbranch_scc1 .LBB0_873
	v_readlane_b32 s24, v255, 13
	s_add_u32 s3, s26, s1
	v_readlane_b32 s25, v255, 14
	v_or_b32_e32 v0, s3, v112
	s_addc_u32 s6, s27, 0
	v_mov_b64_e32 v[16:17], s[24:25]
	v_mad_u64_u32 v[0:1], s[24:25], v0, s7, v[16:17]
	v_mad_i32_i24 v1, s6, v177, v1
	v_lshl_add_u64 v[0:1], v[0:1], 0, v[114:115]
	v_mov_b32_e32 v123, v115
	v_lshl_add_u64 v[18:19], v[0:1], 0, v[122:123]
	v_or_b32_e32 v0, s3, v116
	v_add_co_u32_e32 v20, vcc, s44, v18
	v_mad_u64_u32 v[0:1], s[24:25], v0, s7, v[16:17]
	v_mad_i32_i24 v1, s6, v177, v1
	s_mov_b64 s[24:25], vcc
	v_add_co_u32_e32 v0, vcc, s44, v0
	v_or_b32_e32 v4, s3, v120
	s_nop 0
	v_addc_co_u32_e32 v1, vcc, 0, v1, vcc
	v_mad_u64_u32 v[4:5], s[28:29], v4, s7, v[16:17]
	s_or_b32 s3, s3, 4
	v_mad_i32_i24 v5, s6, v177, v5
	v_add_co_u32_e32 v4, vcc, s44, v4
	v_or_b32_e32 v8, s3, v116
	s_nop 0
	v_addc_co_u32_e32 v5, vcc, 0, v5, vcc
	v_mad_u64_u32 v[8:9], s[28:29], v8, s7, v[16:17]
	v_mad_i32_i24 v9, s6, v177, v9
	v_add_co_u32_e32 v8, vcc, s44, v8
	v_or_b32_e32 v12, s3, v120
	s_nop 0
	v_addc_co_u32_e32 v9, vcc, 0, v9, vcc
	s_mov_b64 s[30:31], 0x1100
	s_waitcnt lgkmcnt(0)
	v_mad_u64_u32 v[12:13], s[28:29], v12, s7, v[16:17]
	v_lshl_add_u64 v[22:23], v[18:19], 0, s[30:31]
	v_mad_i32_i24 v13, s6, v177, v13
	v_add_co_u32_e32 v12, vcc, s44, v12
	v_or_b32_e32 v18, s3, v112
	global_load_dwordx4 v[0:3], v[0:1], off offset:1408
	v_addc_co_u32_e32 v13, vcc, 0, v13, vcc
	v_addc_co_u32_e64 v21, vcc, 0, v19, s[24:25]
	v_mad_u64_u32 v[18:19], s[24:25], v18, s7, v[16:17]
	v_mad_i32_i24 v19, s6, v177, v19
	global_load_dwordx4 v[4:7], v[4:5], off offset:1408
	v_lshl_add_u64 v[18:19], v[18:19], 0, v[114:115]
	v_lshl_add_u64 v[18:19], v[18:19], 0, v[122:123]
	global_load_dwordx4 v[8:11], v[8:9], off offset:1408
	v_or_b32_e32 v190, s1, v116
	global_load_dwordx4 v[12:15], v[12:13], off offset:1408
	s_nop 0
	global_load_dwordx4 v[64:67], v[22:23], off offset:32
	global_load_dwordx4 v[68:71], v[22:23], off offset:64
	global_load_dwordx4 v[72:75], v[20:21], off offset:256
	global_load_dwordx4 v[76:79], v[22:23], off offset:96
	v_lshl_add_u64 v[20:21], v[18:19], 0, s[30:31]
	v_add_co_u32_e32 v22, vcc, s44, v18
	v_or_b32_e32 v18, s26, v110
	v_mad_u64_u32 v[16:17], s[24:25], v18, s7, v[16:17]
	v_mad_i32_i24 v17, s27, v177, v17
	v_lshl_add_u64 v[16:17], v[16:17], 0, v[122:123]
	s_mov_b64 s[24:25], 0x1500
	v_lshl_add_u64 v[124:125], v[16:17], 0, s[24:25]
	v_readlane_b32 s24, v255, 21
	v_readlane_b32 s25, v255, 22
	v_addc_co_u32_e32 v23, vcc, 0, v19, vcc
	s_nop 0
	v_lshl_add_u64 v[16:17], v[124:125], 0, s[24:25]
	global_load_dwordx4 v[80:83], v[20:21], off offset:32
	global_load_dwordx4 v[84:87], v[20:21], off offset:64
	global_load_dwordx4 v[96:99], v[16:17], off offset:96
	global_load_dwordx4 v[100:103], v[16:17], off offset:64
	global_load_dwordx4 v[104:107], v[16:17], off offset:32
	s_nop 0
	global_load_dwordx4 v[16:19], v[16:17], off
	s_nop 0
	global_load_dwordx4 v[88:91], v[22:23], off offset:256
	global_load_dwordx4 v[92:95], v[20:21], off offset:96
	v_mov_b64_e32 v[54:55], v[34:35]
	v_mov_b64_e32 v[58:59], v[38:39]
	v_mov_b64_e32 v[62:63], v[42:43]
	v_mov_b64_e32 v[50:51], v[46:47]
	v_or_b32_e32 v191, 1, v190
	v_or_b32_e32 v192, 4, v190
	v_or_b32_e32 v193, 5, v190
	v_mov_b32_e32 v189, 0xff800000
	v_mov_b32_e32 v188, 0x7f800000
	v_mov_b32_e32 v196, v171
	v_readlane_b32 s6, v255, 20
	v_mov_b64_e32 v[52:53], v[32:33]
	v_mov_b64_e32 v[56:57], v[36:37]
	v_mov_b64_e32 v[60:61], v[40:41]
	v_mov_b64_e32 v[48:49], v[44:45]
	v_mov_b32_e32 v186, 0x7f800000
	v_mov_b32_e32 v184, 0x7f800000
	v_mov_b32_e32 v123, 0x7f800000
	v_mov_b32_e32 v187, 0xff800000
	v_mov_b32_e32 v185, 0xff800000
	v_mov_b32_e32 v183, 0xff800000
	s_mov_b32 s1, s33
	s_waitcnt vmcnt(15)
	v_and_b32_e32 v20, 0xffff0000, v0
	v_lshlrev_b32_e32 v21, 16, v0
	v_and_b32_e32 v0, 0xffff0000, v1
	v_lshlrev_b32_e32 v1, 16, v1
	v_pk_mul_f32 v[128:129], v[0:1], s[58:59] op_sel_hi:[1,0]
	v_and_b32_e32 v0, 0xffff0000, v3
	v_lshlrev_b32_e32 v1, 16, v3
	v_pk_mul_f32 v[132:133], v[0:1], s[58:59] op_sel_hi:[1,0]
	s_waitcnt vmcnt(14)
	v_and_b32_e32 v0, 0xffff0000, v4
	v_lshlrev_b32_e32 v1, 16, v4
	v_pk_mul_f32 v[134:135], v[0:1], s[58:59] op_sel_hi:[1,0]
	v_and_b32_e32 v0, 0xffff0000, v5
	v_lshlrev_b32_e32 v1, 16, v5
	v_pk_mul_f32 v[136:137], v[0:1], s[58:59] op_sel_hi:[1,0]
	v_and_b32_e32 v0, 0xffff0000, v6
	v_lshlrev_b32_e32 v1, 16, v6
	v_pk_mul_f32 v[138:139], v[0:1], s[58:59] op_sel_hi:[1,0]
	v_and_b32_e32 v0, 0xffff0000, v7
	v_lshlrev_b32_e32 v1, 16, v7
	v_pk_mul_f32 v[140:141], v[0:1], s[58:59] op_sel_hi:[1,0]
	s_waitcnt vmcnt(13)
	v_and_b32_e32 v0, 0xffff0000, v8
	v_lshlrev_b32_e32 v1, 16, v8
	v_pk_mul_f32 v[142:143], v[0:1], s[58:59] op_sel_hi:[1,0]
	v_and_b32_e32 v0, 0xffff0000, v9
	v_lshlrev_b32_e32 v1, 16, v9
	v_pk_mul_f32 v[144:145], v[0:1], s[58:59] op_sel_hi:[1,0]
	v_and_b32_e32 v0, 0xffff0000, v10
	v_lshlrev_b32_e32 v1, 16, v10
	v_pk_mul_f32 v[146:147], v[0:1], s[58:59] op_sel_hi:[1,0]
	v_and_b32_e32 v0, 0xffff0000, v11
	v_lshlrev_b32_e32 v1, 16, v11
	v_pk_mul_f32 v[148:149], v[0:1], s[58:59] op_sel_hi:[1,0]
	s_waitcnt vmcnt(12)
	v_and_b32_e32 v0, 0xffff0000, v12
	v_lshlrev_b32_e32 v1, 16, v12
	v_pk_mul_f32 v[150:151], v[0:1], s[58:59] op_sel_hi:[1,0]
	v_and_b32_e32 v0, 0xffff0000, v13
	v_lshlrev_b32_e32 v1, 16, v13
	v_pk_mul_f32 v[152:153], v[0:1], s[58:59] op_sel_hi:[1,0]
	v_and_b32_e32 v0, 0xffff0000, v14
	v_lshlrev_b32_e32 v1, 16, v14
	v_and_b32_e32 v22, 0xffff0000, v2
	v_lshlrev_b32_e32 v23, 16, v2
	v_pk_mul_f32 v[154:155], v[0:1], s[58:59] op_sel_hi:[1,0]
	v_and_b32_e32 v0, 0xffff0000, v15
	v_lshlrev_b32_e32 v1, 16, v15
	v_pk_mul_f32 v[126:127], v[20:21], s[58:59] op_sel_hi:[1,0]
	v_pk_mul_f32 v[130:131], v[22:23], s[58:59] op_sel_hi:[1,0]
	v_pk_mul_f32 v[156:157], v[0:1], s[58:59] op_sel_hi:[1,0]
	s_waitcnt vmcnt(0)

; #define LAS __attribute__((address_space(3)))
; __device__ __forceinline__ void indexer_phase(const bf16_t* PJ, float* rk, unsigned short* SEL, LAS unsigned char* lds) {
;     ...
;             while (kt < nkt) {
;                 const int kn = kt + NWAVE;
;                 if (kn < nkt) {
; #pragma unroll
;                     for (int kk = 0; kk < 4; ++kk) bnxt[kk] = *(const bf16x8*)(kbase + (size_t)(32 * kn) * PROJ_LD + kk * 16);
;                 }
;                 const int key = 32 * kt + r32;
; #pragma unroll
;                 for (int rt = 0; rt < 2; ++rt) {
;                     f32x16 acc = f32x16{};
; #pragma unroll
;                     for (int kk = 0; kk < 4; ++kk) acc = __builtin_amdgcn_mfma_f32_32x32x16_bf16(af[rt][kk], bcur[kk], acc, 0, 0, 0);
; #pragma unroll
;                     for (int qq = 0; qq < 2; ++qq) { float s = 0.f;
; #pragma unroll
;                         for (int e = 0; e < 8; ++e) s += wq[rt][qq][e] * fmaxf(acc[8 * qq + e], 0.f);
;                         ((LAS float*)lds)[(4 * rt + 2 * hi + qq) * 4096 + key] = s;
;                         const bool ok = key <= t0 + 4 * rt + 2 * hi + qq;
;                         rmax[rt][qq] = fmaxf(rmax[rt][qq], ok ? s : -INFINITY); rmin[rt][qq] = fminf(rmin[rt][qq], ok ? s : INFINITY); }
;                 }
; #pragma unroll
;                 for (int kk = 0; kk < 4; ++kk) bcur[kk] = bnxt[kk];
;                 kt = kn;
.LBB0_871:
	s_nop 0
	v_mfma_f32_32x32x16_bf16 v[0:15], v[72:75], v[16:19], 0
	v_add_u32_e32 v197, s6, v110
	v_cmp_gt_i32_e32 vcc, v197, v190
	v_max_f32_e32 v20, v189, v189
	v_max_f32_e32 v21, v188, v188
	v_mfma_f32_32x32x16_bf16 v[0:15], v[64:67], v[104:107], v[0:15]
	v_mfma_f32_32x32x16_bf16 v[0:15], v[68:71], v[100:103], v[0:15]
	v_mfma_f32_32x32x16_bf16 v[0:15], v[76:79], v[96:99], v[0:15]
	s_nop 11
	v_max_f32_e32 v0, v0, v0
	v_max_f32_e32 v22, v1, v1
	v_max_f32_e32 v1, 0, v0
	v_max_f32_e32 v0, 0, v22
	v_max_f32_e32 v2, v2, v2
	v_max_f32_e32 v23, v3, v3
	v_pk_mul_f32 v[0:1], v[126:127], v[0:1]
	v_max_f32_e32 v3, 0, v2
	v_max_f32_e32 v2, 0, v23
	v_add_f32_e32 v1, 0, v1
	v_max_f32_e32 v4, v4, v4
	v_max_f32_e32 v24, v5, v5
	v_pk_mul_f32 v[2:3], v[128:129], v[2:3]
	v_add_f32_e32 v0, v0, v1
	v_max_f32_e32 v5, 0, v4
	v_max_f32_e32 v4, 0, v24
	v_add_f32_e32 v0, v3, v0
	v_max_f32_e32 v6, v6, v6
	v_max_f32_e32 v25, v7, v7
	v_pk_mul_f32 v[4:5], v[130:131], v[4:5]
	v_add_f32_e32 v0, v2, v0
	v_max_f32_e32 v7, 0, v6
	v_max_f32_e32 v6, 0, v25
	v_add_f32_e32 v0, v5, v0
	v_pk_mul_f32 v[6:7], v[132:133], v[6:7]
	v_add_f32_e32 v0, v4, v0
	v_add_f32_e32 v0, v7, v0
	v_add_f32_e32 v2, v6, v0
	v_max_f32_e32 v8, v8, v8
	v_max_f32_e32 v26, v9, v9
	v_cndmask_b32_e32 v0, v2, v178, vcc
	v_cndmask_b32_e32 v1, v2, v179, vcc
	v_max_f32_e32 v9, 0, v8
	v_max_f32_e32 v8, 0, v26
	v_max_f32_e32 v189, v20, v0
	v_min_f32_e32 v188, v21, v1
	s_nop 0
	v_mfma_f32_32x32x16_bf16 v[16:31], v[88:91], v[16:19], 0
	v_mul_f32_e64 v8, v134, v8
	v_mul_f32_e64 v9, v135, v9
	v_cmp_gt_i32_e32 vcc, v197, v191
	v_add_f32_e32 v0, 0, v9
	v_add_f32_e32 v3, v8, v0
	v_max_f32_e32 v0, v10, v10
	v_max_f32_e32 v1, 0, v0
	v_max_f32_e32 v0, v11, v11
	v_mfma_f32_32x32x16_bf16 v[16:31], v[80:83], v[104:107], v[16:31]
	v_max_f32_e32 v0, 0, v0
	v_mul_f32_e64 v0, v136, v0
	v_mul_f32_e64 v1, v137, v1
	v_add_f32_e32 v1, v1, v3
	v_add_f32_e32 v3, v0, v1
	v_max_f32_e32 v0, v12, v12
	v_max_f32_e32 v1, 0, v0
	v_mfma_f32_32x32x16_bf16 v[16:31], v[84:87], v[100:103], v[16:31]
	v_max_f32_e32 v0, v13, v13
	v_max_f32_e32 v0, 0, v0
	v_mul_f32_e64 v0, v138, v0
	v_mul_f32_e64 v1, v139, v1
	v_add_f32_e32 v1, v1, v3
	v_add_f32_e32 v3, v0, v1
	v_max_f32_e32 v0, v14, v14
	s_nop 0
	v_mfma_f32_32x32x16_bf16 v[16:31], v[92:95], v[96:99], v[16:31]
	v_max_f32_e32 v1, 0, v0
	v_max_f32_e32 v0, v15, v15
	v_max_f32_e32 v0, 0, v0
	v_mul_f32_e64 v0, v140, v0
	v_mul_f32_e64 v1, v141, v1
	v_add_f32_e32 v1, v1, v3
	v_add_f32_e32 v0, v0, v1
	ds_write2st64_b32 v196, v2, v0 offset1:64
	v_cndmask_b32_e32 v1, v0, v178, vcc
	v_max_f32_e32 v2, v187, v187
	v_max_f32_e32 v187, v2, v1
	v_cndmask_b32_e32 v0, v0, v179, vcc
	v_max_f32_e32 v1, v186, v186
	v_min_f32_e32 v186, v1, v0
	v_max_f32_e32 v0, v16, v16
	v_max_f32_e32 v1, 0, v0
	v_max_f32_e32 v0, v17, v17
	v_max_f32_e32 v0, 0, v0
	v_pk_mul_f32 v[0:1], v[142:143], v[0:1]
	v_cmp_gt_i32_e32 vcc, v197, v192
	v_add_f32_e32 v1, 0, v1
	v_add_f32_e32 v2, v0, v1
	v_max_f32_e32 v0, v18, v18
	v_max_f32_e32 v1, 0, v0
	v_max_f32_e32 v0, v19, v19
	v_max_f32_e32 v0, 0, v0
	v_pk_mul_f32 v[0:1], v[144:145], v[0:1]
	s_nop 0
	v_add_f32_e32 v1, v1, v2
	v_add_f32_e32 v2, v0, v1
	v_max_f32_e32 v0, v20, v20
	v_max_f32_e32 v1, 0, v0
	v_max_f32_e32 v0, v21, v21
	v_max_f32_e32 v0, 0, v0
	v_pk_mul_f32 v[0:1], v[146:147], v[0:1]
	s_nop 0
	v_add_f32_e32 v1, v1, v2
	v_add_f32_e32 v2, v0, v1
	v_max_f32_e32 v0, v22, v22
	v_max_f32_e32 v1, 0, v0
	v_max_f32_e32 v0, v23, v23
	v_max_f32_e32 v0, 0, v0
	v_pk_mul_f32 v[0:1], v[148:149], v[0:1]
	s_nop 0
	v_add_f32_e32 v1, v1, v2
	v_add_f32_e32 v0, v0, v1
	v_add_u32_e32 v1, 0x10000, v196
	ds_write_b32 v1, v0
	v_cndmask_b32_e32 v1, v0, v178, vcc
	v_max_f32_e32 v2, v185, v185
	v_max_f32_e32 v185, v2, v1
	v_cndmask_b32_e32 v0, v0, v179, vcc
	v_max_f32_e32 v1, v184, v184
	v_min_f32_e32 v184, v1, v0
	v_max_f32_e32 v0, v24, v24
	v_max_f32_e32 v1, 0, v0
	v_max_f32_e32 v0, v25, v25
	v_max_f32_e32 v0, 0, v0
	v_pk_mul_f32 v[0:1], v[150:151], v[0:1]
	v_cmp_gt_i32_e32 vcc, v197, v193
	v_add_f32_e32 v1, 0, v1
	v_add_f32_e32 v2, v0, v1
	v_max_f32_e32 v0, v26, v26
	v_max_f32_e32 v1, 0, v0
	v_max_f32_e32 v0, v27, v27
	v_max_f32_e32 v0, 0, v0
	v_pk_mul_f32 v[0:1], v[152:153], v[0:1]
	s_nop 0
	v_add_f32_e32 v1, v1, v2
	v_add_f32_e32 v2, v0, v1
	v_max_f32_e32 v0, v28, v28
	v_max_f32_e32 v1, 0, v0
	v_max_f32_e32 v0, v29, v29
	v_max_f32_e32 v0, 0, v0
	v_pk_mul_f32 v[0:1], v[154:155], v[0:1]
	s_nop 0
	v_add_f32_e32 v1, v1, v2
	v_add_f32_e32 v2, v0, v1
	v_max_f32_e32 v0, v30, v30
	v_max_f32_e32 v1, 0, v0
	v_max_f32_e32 v0, v31, v31
	v_max_f32_e32 v0, 0, v0
	v_pk_mul_f32 v[0:1], v[156:157], v[0:1]
	s_nop 0
	v_add_f32_e32 v1, v1, v2
	v_add_f32_e32 v0, v0, v1
	v_add_u32_e32 v1, 0x14000, v196
	ds_write_b32 v1, v0
	v_cndmask_b32_e32 v1, v0, v178, vcc
	v_max_f32_e32 v2, v183, v183
	v_max_f32_e32 v183, v2, v1
	v_cndmask_b32_e32 v0, v0, v179, vcc
	v_max_f32_e32 v1, v123, v123
	v_min_f32_e32 v123, v1, v0
	v_add_u32_e32 v196, 0x400, v196
	s_and_b64 vcc, exec, s[24:25]
	s_cbranch_vccnz .LBB0_874
	s_waitcnt vmcnt(0)
	v_mov_b64_e32 v[16:17], v[52:53]
	v_mov_b64_e32 v[106:107], v[58:59]
	v_mov_b64_e32 v[102:103], v[62:63]
	v_mov_b64_e32 v[98:99], v[50:51]
	s_mov_b32 s6, s3
	v_mov_b64_e32 v[18:19], v[54:55]
	v_mov_b64_e32 v[104:105], v[56:57]
	v_mov_b64_e32 v[100:101], v[60:61]
	v_mov_b64_e32 v[96:97], v[48:49]
	s_branch .LBB0_867
